# v15 + barrier before attention: arrive (and L2 writeback by the group's last WG) moved in front of the w_out1/w_gate1 ticket window; only the poll stays at the barrier site
# baseline (speedup 1.0000x reference)
; __device__ __forceinline__ unsigned xb_ld(unsigned* p)              { return __hip_atomic_load(p, __ATOMIC_RELAXED, __HIP_MEMORY_SCOPE_AGENT); }
; __device__ __forceinline__ unsigned xb_add(unsigned* p, unsigned v) { return __hip_atomic_fetch_add(p, v, __ATOMIC_RELAXED, __HIP_MEMORY_SCOPE_AGENT); }
; #define XB_SPIN(cond, bar) do { unsigned _sp = 0; while (cond) { __builtin_amdgcn_s_sleep(1); \
;     if ((++_sp & 255u) == 0u) { if (xb_ld(&(bar)[XB_TMO])) break; if (_sp > XB_SPIN_CAP) { atomicAdd(&(bar)[XB_TMO], 1u); break; } } } } while (0)
; __device__ __forceinline__ void xcd_barrier(const XcdBarrier& b) {
;     asm volatile("s_waitcnt vmcnt(0)" ::: "memory");
;     __syncthreads();
;     if (threadIdx.x == 0) {
;         unsigned* bar = b.bar;
;         __builtin_amdgcn_s_waitcnt(0);
;         unsigned nloc = b.st[0], nx = b.st[1];
;         if (nloc == 0u) { xcd_barrier_complete(bar, b.x, nloc, nx); b.st[0] = nloc; b.st[1] = nx; }
;         const unsigned old = xb_add(&bar[XB_XSUB(b.x)], 1u);
;         const unsigned gen = old / nloc;
;         if (old + 1u == (gen + 1u) * nloc) {
;             __builtin_amdgcn_fence(__ATOMIC_RELEASE, "agent");
;             asm volatile("s_waitcnt vmcnt(0)" ::: "memory");
;             const unsigned og = xb_add(&bar[XB_TOP], 1u);
;             const unsigned tg = og / nx;
;             if (og + 1u == (tg + 1u) * nx) xb_add(&bar[XB_TOPGEN], 1u);
;             else XB_SPIN(xb_ld(&bar[XB_TOPGEN]) == tg, bar);
;             __builtin_amdgcn_fence(__ATOMIC_ACQUIRE, "agent");
;             xb_add(&bar[XB_XGEN(b.x)], 1u);
;             asm volatile("s_waitcnt vmcnt(0)" ::: "memory");
;         } else {
;             XB_SPIN(xb_ld(&bar[XB_XGEN(b.x)]) == gen, bar);
;             __builtin_amdgcn_fence(__ATOMIC_ACQUIRE, "agent");
;             asm volatile("s_waitcnt vmcnt(0)" ::: "memory");
;         }
;     }
;     __syncthreads();
; }
; __global__ void __launch_bounds__(NTHREADS, 2) mk_fwd(Params P) {
;     ...
;     if (IN(7)) {
;         transpose_convert(lds, P.w_out + (size_t)2048 * 2048, WOUT1, 2048, 2048, G, bid);
;         transpose_convert(lds, P.w_gate + (size_t)2048 * 2048, WG1, 2048, 2048, G, bid);
;     }
;     if (IN(7)) attn_phase(lds, Qb, Kb, VTb, Zb, KPART, Y1, G, bid);
.LBB0_570:
	s_waitcnt vmcnt(0)
	s_barrier
	s_mov_b64 s[100:101], s[16:17]
	s_add_u32 s24, s40, 0x2000000
	s_addc_u32 s25, s41, 0
	s_add_u32 s22, s40, 0x2800000
	s_addc_u32 s23, s41, 0
	s_movk_i32 s98, 0x100
	v_mov_b32_e32 v46, 0x20008
	s_add_u32 s10, s54, 0xa000
	s_addc_u32 s11, s55, 0
	s_and_saveexec_b64 s[18:19], s[12:13]
	s_cbranch_execz .Ldyn7_nofirst
	s_and_b32 s99, s2, 7
	s_lshl_b32 s99, s99, 6
	s_add_i32 s99, s99, 0x8000
	v_mov_b32_e32 v250, s99
	v_mov_b32_e32 v252, 1
	v_mov_b32_e32 v253, 0x2000c
	ds_read_b32 v254, v253
	s_waitcnt lgkmcnt(0)
	v_readfirstlane_b32 s99, v254
	s_cmp_eq_u32 s99, 1
	s_cbranch_scc1 .Lgg6_f
	buffer_wbl2 sc1
	s_waitcnt vmcnt(0)
.Lgg6_f:
	global_atomic_add v251, v250, v252, s[54:55] offset:40 sc0
	v_mov_b32_e32 v0, 0
	v_mov_b32_e32 v47, 1
	global_atomic_add v47, v0, v47, s[10:11] sc0
	s_waitcnt vmcnt(0)
	v_readfirstlane_b32 s99, v251
	s_cmp_eq_u32 s99, 31
	s_cbranch_scc0 .Lgg6_n
	buffer_wbl2 sc1
	s_waitcnt vmcnt(0)
	v_mov_b32_e32 v253, 0x82c0
	global_atomic_add v253, v252, s[54:55]
.Lgg6_n:
.Ldyn7_nofirst:
	s_or_b64 exec, exec, s[18:19]

; __device__ __forceinline__ unsigned xb_ld(unsigned* p)              { return __hip_atomic_load(p, __ATOMIC_RELAXED, __HIP_MEMORY_SCOPE_AGENT); }
; __device__ __forceinline__ unsigned xb_add(unsigned* p, unsigned v) { return __hip_atomic_fetch_add(p, v, __ATOMIC_RELAXED, __HIP_MEMORY_SCOPE_AGENT); }
; #define XB_SPIN(cond, bar) do { unsigned _sp = 0; while (cond) { __builtin_amdgcn_s_sleep(1); \
;     if ((++_sp & 255u) == 0u) { if (xb_ld(&(bar)[XB_TMO])) break; if (_sp > XB_SPIN_CAP) { atomicAdd(&(bar)[XB_TMO], 1u); break; } } } } while (0)
; __device__ __forceinline__ void xcd_barrier(const XcdBarrier& b) {
;     asm volatile("s_waitcnt vmcnt(0)" ::: "memory");
;     __syncthreads();
;     if (threadIdx.x == 0) {
;         unsigned* bar = b.bar;
;         __builtin_amdgcn_s_waitcnt(0);
;         unsigned nloc = b.st[0], nx = b.st[1];
;         if (nloc == 0u) { xcd_barrier_complete(bar, b.x, nloc, nx); b.st[0] = nloc; b.st[1] = nx; }
;         const unsigned old = xb_add(&bar[XB_XSUB(b.x)], 1u);
;         const unsigned gen = old / nloc;
;         if (old + 1u == (gen + 1u) * nloc) {
;             __builtin_amdgcn_fence(__ATOMIC_RELEASE, "agent");
;             asm volatile("s_waitcnt vmcnt(0)" ::: "memory");
;             const unsigned og = xb_add(&bar[XB_TOP], 1u);
;             const unsigned tg = og / nx;
;             if (og + 1u == (tg + 1u) * nx) xb_add(&bar[XB_TOPGEN], 1u);
;             else XB_SPIN(xb_ld(&bar[XB_TOPGEN]) == tg, bar);
;             __builtin_amdgcn_fence(__ATOMIC_ACQUIRE, "agent");
;             xb_add(&bar[XB_XGEN(b.x)], 1u);
;             asm volatile("s_waitcnt vmcnt(0)" ::: "memory");
;         } else {
;             XB_SPIN(xb_ld(&bar[XB_XGEN(b.x)]) == gen, bar);
;             __builtin_amdgcn_fence(__ATOMIC_ACQUIRE, "agent");
;             asm volatile("s_waitcnt vmcnt(0)" ::: "memory");
;         }
;     }
;     __syncthreads();
; }
.LBB0_571:
	s_cmp_gt_i32 s43, 7
	s_cselect_b64 s[4:5], -1, 0
	s_and_b64 s[6:7], s[16:17], s[4:5]
	s_andn2_b64 vcc, exec, s[6:7]
	s_cbranch_vccnz .LBB0_621
	s_waitcnt vmcnt(0)
	s_waitcnt vmcnt(0) lgkmcnt(0)
	s_barrier
	s_and_saveexec_b64 s[6:7], s[12:13]
	s_cbranch_execz .LBB0_620
	v_mov_b32_e32 v253, 0x82c0
	s_mov_b32 s99, 0
